# gating: T tile double-buffered in LDS (one barrier per unit) and the LayerNorm outputs converted to bf16 with v_cvt_pk_bf16_f32 pairs instead of the per-value bit trick
# speedup vs baseline: 1.0145x; 1.0040x over previous
.LBB0_44:
	s_waitcnt lgkmcnt(0)
	s_barrier
	ds_read_b128 v[4:7], v136
	ds_read_b128 v[138:141], v136 offset:32
	s_waitcnt lgkmcnt(1)
	v_mfma_f32_32x32x16_bf16 v[0:15], v[4:7], v[0:3], 0
	s_ashr_i32 s26, s13, 3
	s_ashr_i32 s27, s26, 31
	s_lshl_b64 s[26:27], s[26:27], 18
	s_lshl_b32 s72, s19, 1
	s_andn2_b64 vcc, exec, s[22:23]
	s_waitcnt lgkmcnt(0)
	v_mfma_f32_32x32x16_bf16 v[0:15], v[138:141], v[60:63], v[0:15]
	ds_read_b128 v[60:63], v136 offset:64
	s_waitcnt lgkmcnt(0)
	v_mfma_f32_32x32x16_bf16 v[0:15], v[60:63], v[64:67], v[0:15]
	ds_read_b128 v[60:63], v136 offset:96
	v_mov_b64_e32 v[64:65], v[76:77]
	v_mov_b64_e32 v[66:67], v[78:79]
	s_waitcnt lgkmcnt(0)
	v_mfma_f32_32x32x16_bf16 v[0:15], v[60:63], v[52:55], v[0:15]
	ds_read_b128 v[52:55], v136 offset:128
	v_mov_b64_e32 v[60:61], v[72:73]
	v_mov_b64_e32 v[62:63], v[74:75]
	s_waitcnt lgkmcnt(0)
	v_mfma_f32_32x32x16_bf16 v[0:15], v[52:55], v[56:59], v[0:15]
	ds_read_b128 v[52:55], v136 offset:160
	v_mov_b64_e32 v[56:57], v[84:85]
	v_mov_b64_e32 v[58:59], v[86:87]
	s_waitcnt lgkmcnt(0)
	v_mfma_f32_32x32x16_bf16 v[0:15], v[52:55], v[48:51], v[0:15]
	ds_read_b128 v[48:51], v136 offset:192
	v_mov_b64_e32 v[52:53], v[80:81]
	v_mov_b64_e32 v[54:55], v[82:83]
	s_waitcnt lgkmcnt(0)
	v_mfma_f32_32x32x16_bf16 v[0:15], v[48:51], v[44:47], v[0:15]
	ds_read_b128 v[44:47], v136 offset:224
	v_xor_b32_e32 v136, 0x8000, v136
	v_mov_b64_e32 v[48:49], v[88:89]
	v_mov_b64_e32 v[50:51], v[90:91]
	s_waitcnt lgkmcnt(0)
	v_mfma_f32_32x32x16_bf16 v[0:15], v[44:47], v[40:43], v[0:15]
	v_lshlrev_b32_e32 v42, 16, v124
	v_lshl_add_u64 v[40:41], v[112:113], 0, s[26:27]
	v_lshl_add_u64 v[40:41], v[40:41], 0, s[72:73]
	v_mov_b64_e32 v[44:45], v[92:93]
	v_mov_b64_e32 v[46:47], v[94:95]
	s_nop 10
	v_add_f32_e32 v0, v137, v0
	v_mul_f32_e32 v0, v0, v42
	v_and_b32_e32 v42, 0xffff0000, v124
	v_add_f32_e32 v1, v137, v1
	v_mul_f32_e32 v1, v1, v42
	v_cvt_pk_bf16_f32 v172, v0, v1
	v_lshlrev_b32_e32 v0, 16, v125
	v_add_f32_e32 v1, v137, v2
	v_mul_f32_e32 v0, v1, v0
	v_and_b32_e32 v1, 0xffff0000, v125
	v_add_f32_e32 v2, v137, v3
	v_mul_f32_e32 v1, v2, v1
	v_lshlrev_b32_e32 v2, 16, v122
	v_add_f32_e32 v3, v137, v4
	v_mul_f32_e32 v2, v3, v2
	v_and_b32_e32 v3, 0xffff0000, v122
	v_add_f32_e32 v4, v137, v5
	v_cvt_pk_bf16_f32 v173, v0, v1
	v_lshl_add_u64 v[0:1], v[40:41], 0, v[160:161]
	v_mul_f32_e32 v3, v4, v3
	v_cvt_pk_bf16_f32 v176, v2, v3
	v_lshlrev_b32_e32 v3, 16, v123
	v_add_f32_e32 v4, v137, v6
	v_mul_f32_e32 v3, v4, v3
	v_and_b32_e32 v4, 0xffff0000, v123
	v_add_f32_e32 v5, v137, v7
	v_mul_f32_e32 v4, v5, v4
	v_cvt_pk_bf16_f32 v177, v3, v4
	v_lshlrev_b32_e32 v2, 16, v120
	v_add_f32_e32 v3, v137, v8
	v_mul_f32_e32 v2, v3, v2
	v_and_b32_e32 v3, 0xffff0000, v120
	v_add_f32_e32 v4, v137, v9
	v_mul_f32_e32 v3, v4, v3
	v_cvt_pk_bf16_f32 v174, v2, v3
	v_lshlrev_b32_e32 v3, 16, v121
	v_add_f32_e32 v4, v137, v10
	v_mul_f32_e32 v3, v4, v3
	v_and_b32_e32 v4, 0xffff0000, v121
	v_add_f32_e32 v5, v137, v11
	v_mul_f32_e32 v4, v5, v4
	v_cvt_pk_bf16_f32 v175, v3, v4
	v_lshlrev_b32_e32 v2, 16, v106
	v_add_f32_e32 v3, v137, v12
	v_mul_f32_e32 v2, v3, v2
	v_and_b32_e32 v3, 0xffff0000, v106
	v_add_f32_e32 v4, v137, v13
	v_mul_f32_e32 v3, v4, v3
	v_cvt_pk_bf16_f32 v178, v2, v3
	v_lshlrev_b32_e32 v3, 16, v107
	v_add_f32_e32 v4, v137, v14
	v_mul_f32_e32 v3, v4, v3
	v_and_b32_e32 v4, 0xffff0000, v107
	v_add_f32_e32 v5, v137, v15
	v_mul_f32_e32 v4, v5, v4
	v_cvt_pk_bf16_f32 v179, v3, v4
	s_nop 1
	v_permlane32_swap_b32_e32 v172, v174
	v_permlane32_swap_b32_e32 v173, v175
	v_permlane32_swap_b32_e32 v176, v178
	v_permlane32_swap_b32_e32 v177, v179
	global_store_dwordx4 v[0:1], v[172:175], off offset:1024
	global_store_dwordx4 v[0:1], v[176:179], off offset:1040
	s_waitcnt vmcnt(2)
	v_permlane32_swap_b32_e32 v126, v128
	v_permlane32_swap_b32_e32 v127, v129
	v_permlane32_swap_b32_e32 v130, v132
	v_permlane32_swap_b32_e32 v131, v133
	v_mov_b64_e32 v[0:1], v[68:69]
	v_mov_b64_e32 v[40:41], v[96:97]
	v_mov_b64_e32 v[124:125], v[126:127]
	v_mov_b64_e32 v[122:123], v[130:131]
	v_mov_b64_e32 v[120:121], v[128:129]
	v_mov_b64_e32 v[106:107], v[132:133]
	v_mov_b64_e32 v[2:3], v[70:71]
	v_mov_b64_e32 v[42:43], v[98:99]
	v_xor_b32_e32 v134, 0x8000, v134
	v_xor_b32_e32 v135, 0x8000, v135
	s_cbranch_vccnz .LBB0_51
.LBB0_45:
	s_and_b32 s22, s3, 7
	s_lshl_b32 s72, s22, 8
	s_waitcnt vmcnt(23)
	v_add_f32_e32 v90, v28, v30
	v_add_f32_e32 v91, v29, v31
	s_nop 1
	v_add_f32_dpp v90, v90, v90 quad_perm:[1,0,3,2] row_mask:0xf bank_mask:0xf
	v_add_f32_dpp v91, v91, v91 quad_perm:[1,0,3,2] row_mask:0xf bank_mask:0xf
	s_nop 1
	v_add_f32_dpp v90, v90, v90 quad_perm:[2,3,0,1] row_mask:0xf bank_mask:0xf
	v_add_f32_dpp v91, v91, v91 quad_perm:[2,3,0,1] row_mask:0xf bank_mask:0xf
	s_nop 0
	s_nop 0
	v_mul_f32_e32 v115, 0x3b000000, v90
	s_lshl_b32 s19, s22, 6
	v_mul_f32_e32 v115, v115, v115
	s_mov_b32 s22, 0x3b000000
	v_fma_f32 v91, v91, s22, -v115
	v_max_f32_e32 v91, 0, v91
	v_add_f32_e32 v91, 0x358637bd, v91
	v_rsq_f32_e32 v91, v91
	s_waitcnt vmcnt(21)
	v_lshlrev_b32_e32 v92, 16, v36
	v_lshlrev_b32_e32 v94, 16, v37
	v_lshlrev_b32_e32 v96, 16, v38
	v_and_b32_e32 v93, 0xffff0000, v36
	v_and_b32_e32 v95, 0xffff0000, v37
	v_and_b32_e32 v97, 0xffff0000, v38
	v_fmac_f32_e32 v92, 0xbb000000, v90
	v_fmac_f32_e32 v94, 0xbb000000, v90
	v_fmac_f32_e32 v96, 0xbb000000, v90
	v_lshlrev_b32_e32 v98, 16, v39
	v_fmac_f32_e32 v93, 0xbb000000, v90
	v_fmac_f32_e32 v95, 0xbb000000, v90
	v_fmac_f32_e32 v97, 0xbb000000, v90
	v_mul_f32_e32 v88, v92, v91
	v_mul_f32_e32 v92, v94, v91
	v_mul_f32_e32 v94, v96, v91
	v_fmac_f32_e32 v98, 0xbb000000, v90
	v_mul_f32_e32 v89, v93, v91
	v_mul_f32_e32 v93, v95, v91
	v_mul_f32_e32 v95, v97, v91
	v_and_b32_e32 v99, 0xffff0000, v39
	v_mul_f32_e32 v96, v98, v91
	v_fmac_f32_e32 v99, 0xbb000000, v90
	v_mul_f32_e32 v97, v99, v91
	s_mov_b32 s13, s3
	s_waitcnt vmcnt(0)
	v_fma_f32 v68, v88, v218, v234
	v_fma_f32 v69, v89, v219, v235
	v_fma_f32 v12, v94, v222, v238
	v_fma_f32 v70, v92, v220, v236
	v_fma_f32 v71, v93, v221, v237
	v_fma_f32 v13, v95, v223, v239
	v_fma_f32 v14, v96, v224, v240
	v_cvt_pk_bf16_f32 v180, v68, v69
	ds_write_b16 v134, v180
	ds_write_b16_d16_hi v135, v180 offset:272
	v_cvt_pk_bf16_f32 v181, v70, v71
	ds_write_b16 v134, v181 offset:544
	ds_write_b16_d16_hi v135, v181 offset:816
	v_cvt_pk_bf16_f32 v182, v12, v13
	ds_write_b16 v134, v182 offset:1088
	ds_write_b16_d16_hi v135, v182 offset:1360
	v_fma_f32 v15, v97, v225, v241
	v_cvt_pk_bf16_f32 v183, v14, v15
	ds_write_b16 v134, v183 offset:1632
	ds_write_b16_d16_hi v135, v183 offset:1904
	v_lshlrev_b32_e32 v12, 16, v32
	v_fmac_f32_e32 v12, 0xbb000000, v90
	v_mul_f32_e32 v12, v12, v91
	v_fma_f32 v4, v12, v226, v242
	v_and_b32_e32 v8, 0xffff0000, v32
	v_fmac_f32_e32 v8, 0xbb000000, v90
	v_mul_f32_e32 v8, v8, v91
	v_fma_f32 v5, v8, v227, v243
	v_cvt_pk_bf16_f32 v184, v4, v5
	ds_write_b16 v134, v184 offset:2176
	ds_write_b16_d16_hi v135, v184 offset:2448
	v_lshlrev_b32_e32 v4, 16, v33
	v_fmac_f32_e32 v4, 0xbb000000, v90
	v_and_b32_e32 v5, 0xffff0000, v33
	v_mul_f32_e32 v4, v4, v91
	v_fmac_f32_e32 v5, 0xbb000000, v90
	v_fma_f32 v4, v4, v228, v244
	v_mul_f32_e32 v5, v5, v91
	v_fma_f32 v7, v5, v229, v245
	v_cvt_pk_bf16_f32 v185, v4, v7
	ds_write_b16 v134, v185 offset:2720
	ds_write_b16_d16_hi v135, v185 offset:2992
	v_lshlrev_b32_e32 v4, 16, v34
	v_fmac_f32_e32 v4, 0xbb000000, v90
	v_mul_f32_e32 v4, v4, v91
	v_and_b32_e32 v5, 0xffff0000, v34
	v_fma_f32 v4, v4, v230, v246
	v_fmac_f32_e32 v5, 0xbb000000, v90
	v_mul_f32_e32 v5, v5, v91
	v_fma_f32 v5, v5, v231, v247
	v_cvt_pk_bf16_f32 v186, v4, v5
	ds_write_b16 v134, v186 offset:3264
	ds_write_b16_d16_hi v135, v186 offset:3536
	v_lshlrev_b32_e32 v4, 16, v35
	v_fmac_f32_e32 v4, 0xbb000000, v90
	v_and_b32_e32 v5, 0xffff0000, v35
	v_mul_f32_e32 v4, v4, v91
	v_fmac_f32_e32 v5, 0xbb000000, v90
	v_fma_f32 v4, v4, v232, v248
	v_mul_f32_e32 v5, v5, v91
	v_fma_f32 v87, v5, v233, v249
	v_cvt_pk_bf16_f32 v187, v4, v87
	ds_write_b16 v134, v187 offset:3808
	ds_write_b16_d16_hi v135, v187 offset:4080
	s_branch .LBB0_47
